# counted vmcnt waits in P1's roll-copy loops (each store waits only for the load that feeds it)
# baseline (speedup 1.0000x reference)
.LBB0_164:
	v_add_u32_e32 v2, s16, v10
	v_mul_hi_i32 v4, v2, s19
	v_add_u32_e32 v4, v4, v2
	v_add_u32_e32 v3, s18, v10
	v_lshrrev_b32_e32 v5, 31, v4
	v_ashrrev_i32_e32 v4, 10, v4
	v_add_u32_e32 v4, v4, v5
	v_mul_hi_i32 v5, v3, s19
	v_add_u32_e32 v5, v5, v3
	v_lshrrev_b32_e32 v6, 31, v5
	v_ashrrev_i32_e32 v5, 10, v5
	v_add_u32_e32 v5, v5, v6
	v_cmp_gt_i32_e32 vcc, s15, v3
	v_mad_i32_i24 v2, v4, s20, v2
	s_nop 0
	v_cndmask_b32_e32 v8, 0, v5, vcc
	v_mad_i32_i24 v3, v8, s20, v3
	v_mul_hi_i32_i24_e32 v5, 0x780, v4
	v_mul_i32_i24_e32 v4, 0x780, v4
	v_cndmask_b32_e32 v6, 0, v3, vcc
	v_ashrrev_i32_e32 v3, 31, v2
	v_lshlrev_b64 v[18:19], 4, v[4:5]
	v_lshl_add_u64 v[4:5], s[88:89], 0, v[18:19]
	v_lshlrev_b64 v[20:21], 4, v[2:3]
	v_mul_hi_i32_i24_e32 v9, 0x780, v8
	v_mul_i32_i24_e32 v8, 0x780, v8
	v_ashrrev_i32_e32 v7, 31, v6
	v_lshl_add_u64 v[2:3], v[4:5], 0, v[20:21]
	v_lshl_add_u64 v[4:5], v[8:9], 4, s[88:89]
	v_lshl_add_u64 v[4:5], v[6:7], 4, v[4:5]
	global_load_dwordx4 v[12:15], v[2:3], off offset:2048
	s_nop 0
	global_load_dwordx4 v[2:5], v[4:5], off offset:2048
	v_lshl_add_u64 v[18:19], s[4:5], 0, v[18:19]
	v_lshl_add_u64 v[18:19], v[18:19], 0, v[20:21]
	s_waitcnt vmcnt(1)
	global_store_dwordx4 v[18:19], v[12:15], off
	s_waitcnt vmcnt(1)
	s_and_saveexec_b64 s[12:13], vcc
	s_cbranch_execz .LBB0_163
	v_lshl_add_u64 v[8:9], v[8:9], 4, s[4:5]
	v_lshl_add_u64 v[6:7], v[6:7], 4, v[8:9]
	global_store_dwordx4 v[6:7], v[2:5], off
	s_branch .LBB0_163

.LBB0_200:
	v_add_u32_e32 v3, s17, v1
	v_mul_hi_i32 v2, v3, s20
	v_add_u32_e32 v2, v2, v3
	v_lshrrev_b32_e32 v4, 31, v2
	v_ashrrev_i32_e32 v2, 11, v2
	v_add_u32_e32 v5, s19, v1
	v_add_u32_e32 v2, v2, v4
	v_mad_i32_i24 v4, v2, s21, v3
	v_mul_hi_i32 v3, v5, s20
	v_add_u32_e32 v3, v3, v5
	v_lshrrev_b32_e32 v6, 31, v3
	v_ashrrev_i32_e32 v3, 11, v3
	v_add_u32_e32 v3, v3, v6
	v_cmp_gt_i32_e32 vcc, s16, v5
	s_nop 1
	v_cndmask_b32_e32 v6, 0, v3, vcc
	v_mad_i32_i24 v3, v6, s21, v5
	v_cndmask_b32_e32 v8, 0, v3, vcc
	v_ashrrev_i32_e32 v3, 31, v2
	v_lshlrev_b64 v[2:3], 12, v[2:3]
	v_ashrrev_i32_e32 v5, 31, v4
	v_ashrrev_i32_e32 v7, 31, v6
	v_ashrrev_i32_e32 v9, 31, v8
	v_lshl_add_u64 v[2:3], v[2:3], 0, v[4:5]
	v_lshlrev_b64 v[4:5], 12, v[6:7]
	v_lshl_add_u64 v[4:5], v[4:5], 0, v[8:9]
	v_lshlrev_b64 v[20:21], 4, v[2:3]
	v_lshlrev_b64 v[10:11], 4, v[4:5]
	v_lshl_add_u64 v[2:3], s[84:85], 0, v[20:21]
	v_lshl_add_u64 v[4:5], s[84:85], 0, v[10:11]
	global_load_dwordx4 v[12:15], v[2:3], off offset:512
	s_nop 0
	global_load_dwordx4 v[2:5], v[4:5], off offset:512
	v_lshl_add_u64 v[6:7], s[86:87], 0, v[20:21]
	v_lshl_add_u64 v[8:9], s[86:87], 0, v[10:11]
	global_load_dwordx4 v[16:19], v[6:7], off offset:512
	s_nop 0
	global_load_dwordx4 v[6:9], v[8:9], off offset:512
	v_lshl_add_u64 v[22:23], s[4:5], 0, v[20:21]
	s_waitcnt vmcnt(3)
	global_store_dwordx4 v[22:23], v[12:15], off
	s_nop 1
	v_lshl_add_u64 v[12:13], s[6:7], 0, v[20:21]
	s_waitcnt vmcnt(2)
	global_store_dwordx4 v[12:13], v[16:19], off
	s_waitcnt vmcnt(2)
	s_and_saveexec_b64 s[14:15], vcc
	s_cbranch_execz .LBB0_199
	v_lshl_add_u64 v[12:13], s[4:5], 0, v[10:11]
	v_lshl_add_u64 v[10:11], s[6:7], 0, v[10:11]
	global_store_dwordx4 v[12:13], v[2:5], off
	global_store_dwordx4 v[10:11], v[6:9], off
	s_branch .LBB0_199
